# MLA vmcnt+K swizzle fix, w_in transposer loads batched, MIX1+MIX2 epilogues pipelined
# speedup vs baseline: 1.0198x; 1.0114x over previous
; #define LAS __attribute__((address_space(3)))
; template <int KIND> __device__ __forceinline__ int srcmap(int n) {
;     if constexpr (KIND == 1) {
;         if (n < 4096) return n;
;         if (n < 4160) { const int j = n - 4096; return 4096 + (j & 1) * 32 + (j >> 1); }
;         if (n < 4352) return -1;
;         return n - 192;
; template <int KIND> __device__ __forceinline__ void tr_item(const float* __restrict__ W, int K, int Nsrc, const float* __restrict__ gk, bf16_t* WT, LAS float* scr, int item, int nblk, int lane) {
;     const int kb = item / nblk, nb = item - kb * nblk, k0 = 64 * kb, n0 = 32 * nb;
;     const int src = srcmap<KIND>(n0 + (lane & 31));
; #pragma unroll 8
;     for (int i = 0; i < 32; ++i) { const int kk = 2 * i + (lane >> 5); float v = 0.f; if (src >= 0) v = __builtin_nontemporal_load(&W[(size_t)(k0 + kk) * Nsrc + src]); if (gk) v *= gk[k0 + kk]; scr[kk * 33 + (lane & 31)] = v; }
;     asm volatile("s_waitcnt lgkmcnt(0)" ::: "memory");
.LBB0_135:
	v_mov_b64_e32 v[100:101], 0
	v_mov_b64_e32 v[102:103], 0
	v_mov_b64_e32 v[104:105], 0
	v_mov_b64_e32 v[106:107], 0
	v_mov_b64_e32 v[108:109], 0
	v_mov_b64_e32 v[110:111], 0
	v_mov_b64_e32 v[112:113], 0
	v_mov_b64_e32 v[114:115], 0
	v_mov_b64_e32 v[116:117], 0
	v_mov_b64_e32 v[118:119], 0
	v_mov_b64_e32 v[120:121], 0
	v_mov_b64_e32 v[122:123], 0
	v_mov_b64_e32 v[124:125], 0
	v_mov_b64_e32 v[126:127], 0
	v_mov_b64_e32 v[128:129], 0
	v_mov_b64_e32 v[130:131], 0
	s_and_saveexec_b64 s[34:35], vcc
	s_cbranch_execz .Lp0_win_noload
	v_lshl_add_u64 v[40:41], v[22:23], 0, s[30:31]
	global_load_dword v100, v[40:41], off nt
	v_lshl_add_u64 v[40:41], v[20:21], 0, s[30:31]
	global_load_dword v101, v[40:41], off nt
	v_lshl_add_u64 v[40:41], v[18:19], 0, s[30:31]
	global_load_dword v102, v[40:41], off nt
	v_lshl_add_u64 v[40:41], v[16:17], 0, s[30:31]
	global_load_dword v103, v[40:41], off nt
	v_lshl_add_u64 v[40:41], v[14:15], 0, s[30:31]
	global_load_dword v104, v[40:41], off nt
	v_lshl_add_u64 v[40:41], v[12:13], 0, s[30:31]
	global_load_dword v105, v[40:41], off nt
	v_lshl_add_u64 v[40:41], v[10:11], 0, s[30:31]
	global_load_dword v106, v[40:41], off nt
	v_lshl_add_u64 v[40:41], v[8:9], 0, s[30:31]
	global_load_dword v107, v[40:41], off nt
	s_add_u32 s30, s30, 0x81000
	s_addc_u32 s31, s31, 0
	v_lshl_add_u64 v[40:41], v[22:23], 0, s[30:31]
	global_load_dword v108, v[40:41], off nt
	v_lshl_add_u64 v[40:41], v[20:21], 0, s[30:31]
	global_load_dword v109, v[40:41], off nt
	v_lshl_add_u64 v[40:41], v[18:19], 0, s[30:31]
	global_load_dword v110, v[40:41], off nt
	v_lshl_add_u64 v[40:41], v[16:17], 0, s[30:31]
	global_load_dword v111, v[40:41], off nt
	v_lshl_add_u64 v[40:41], v[14:15], 0, s[30:31]
	global_load_dword v112, v[40:41], off nt
	v_lshl_add_u64 v[40:41], v[12:13], 0, s[30:31]
	global_load_dword v113, v[40:41], off nt
	v_lshl_add_u64 v[40:41], v[10:11], 0, s[30:31]
	global_load_dword v114, v[40:41], off nt
	v_lshl_add_u64 v[40:41], v[8:9], 0, s[30:31]
	global_load_dword v115, v[40:41], off nt
	s_add_u32 s30, s30, 0x81000
	s_addc_u32 s31, s31, 0
	v_lshl_add_u64 v[40:41], v[22:23], 0, s[30:31]
	global_load_dword v116, v[40:41], off nt
	v_lshl_add_u64 v[40:41], v[20:21], 0, s[30:31]
	global_load_dword v117, v[40:41], off nt
	v_lshl_add_u64 v[40:41], v[18:19], 0, s[30:31]
	global_load_dword v118, v[40:41], off nt
	v_lshl_add_u64 v[40:41], v[16:17], 0, s[30:31]
	global_load_dword v119, v[40:41], off nt
	v_lshl_add_u64 v[40:41], v[14:15], 0, s[30:31]
	global_load_dword v120, v[40:41], off nt
	v_lshl_add_u64 v[40:41], v[12:13], 0, s[30:31]
	global_load_dword v121, v[40:41], off nt
	v_lshl_add_u64 v[40:41], v[10:11], 0, s[30:31]
	global_load_dword v122, v[40:41], off nt
	v_lshl_add_u64 v[40:41], v[8:9], 0, s[30:31]
	global_load_dword v123, v[40:41], off nt
	s_add_u32 s30, s30, 0x81000
	s_addc_u32 s31, s31, 0
	v_lshl_add_u64 v[40:41], v[22:23], 0, s[30:31]
	global_load_dword v124, v[40:41], off nt
	v_lshl_add_u64 v[40:41], v[20:21], 0, s[30:31]
	global_load_dword v125, v[40:41], off nt
	v_lshl_add_u64 v[40:41], v[18:19], 0, s[30:31]
	global_load_dword v126, v[40:41], off nt
	v_lshl_add_u64 v[40:41], v[16:17], 0, s[30:31]
	global_load_dword v127, v[40:41], off nt
	v_lshl_add_u64 v[40:41], v[14:15], 0, s[30:31]
	global_load_dword v128, v[40:41], off nt
	v_lshl_add_u64 v[40:41], v[12:13], 0, s[30:31]
	global_load_dword v129, v[40:41], off nt
	v_lshl_add_u64 v[40:41], v[10:11], 0, s[30:31]
	global_load_dword v130, v[40:41], off nt
	v_lshl_add_u64 v[40:41], v[8:9], 0, s[30:31]
	global_load_dword v131, v[40:41], off nt
	s_add_u32 s30, s30, 0x81000
	s_addc_u32 s31, s31, 0
	s_branch .Lp0_win_loaded
.Lp0_win_noload:
	s_mov_b64 s[30:31], 0x204000
.Lp0_win_loaded:
	s_or_b64 exec, exec, s[34:35]
	s_waitcnt vmcnt(31)
	ds_write_b32 v2, v100 offset:0
	s_waitcnt vmcnt(30)
	ds_write_b32 v2, v101 offset:264
	s_waitcnt vmcnt(29)
	ds_write_b32 v2, v102 offset:528
	s_waitcnt vmcnt(28)
	ds_write_b32 v2, v103 offset:792
	s_waitcnt vmcnt(27)
	ds_write_b32 v2, v104 offset:1056
	s_waitcnt vmcnt(26)
	ds_write_b32 v2, v105 offset:1320
	s_waitcnt vmcnt(25)
	ds_write_b32 v2, v106 offset:1584
	s_waitcnt vmcnt(24)
	ds_write_b32 v2, v107 offset:1848
	s_waitcnt vmcnt(23)
	ds_write_b32 v2, v108 offset:2112
	s_waitcnt vmcnt(22)
	ds_write_b32 v2, v109 offset:2376
	s_waitcnt vmcnt(21)
	ds_write_b32 v2, v110 offset:2640
	s_waitcnt vmcnt(20)
	ds_write_b32 v2, v111 offset:2904
	s_waitcnt vmcnt(19)
	ds_write_b32 v2, v112 offset:3168
	s_waitcnt vmcnt(18)
	ds_write_b32 v2, v113 offset:3432
	s_waitcnt vmcnt(17)
	ds_write_b32 v2, v114 offset:3696
	s_waitcnt vmcnt(16)
	ds_write_b32 v2, v115 offset:3960
	s_waitcnt vmcnt(15)
	ds_write_b32 v2, v116 offset:4224
	s_waitcnt vmcnt(14)
	ds_write_b32 v2, v117 offset:4488
	s_waitcnt vmcnt(13)
	ds_write_b32 v2, v118 offset:4752
	s_waitcnt vmcnt(12)
	ds_write_b32 v2, v119 offset:5016
	s_waitcnt vmcnt(11)
	ds_write_b32 v2, v120 offset:5280
	s_waitcnt vmcnt(10)
	ds_write_b32 v2, v121 offset:5544
	s_waitcnt vmcnt(9)
	ds_write_b32 v2, v122 offset:5808
	s_waitcnt vmcnt(8)
	ds_write_b32 v2, v123 offset:6072
	s_waitcnt vmcnt(7)
	ds_write_b32 v2, v124 offset:6336
	s_waitcnt vmcnt(6)
	ds_write_b32 v2, v125 offset:6600
	s_waitcnt vmcnt(5)
	ds_write_b32 v2, v126 offset:6864
	s_waitcnt vmcnt(4)
	ds_write_b32 v2, v127 offset:7128
	s_waitcnt vmcnt(3)
	ds_write_b32 v2, v128 offset:7392
	s_waitcnt vmcnt(2)
	ds_write_b32 v2, v129 offset:7656
	s_waitcnt vmcnt(1)
	ds_write_b32 v2, v130 offset:7920
	s_waitcnt vmcnt(0)
	ds_write_b32 v2, v131 offset:8184
	v_add_u32_e32 v2, 0x2100, v2
	s_branch .LBB0_22

; __device__ __forceinline__ int v_st(int k, int c) { const int kk = (k & ~0xC) | ((k & 4) << 1) | ((k & 8) >> 1); return ((kk >> 3) * 4 + (c >> 5)) * 512 + ((kk & 7) * 32 + (c & 31)) * 2; }
; __device__ __forceinline__ int v_rd_base(int lane) { return ((lane & 3) << 3) | (((lane >> 2) & 3) << 6) | (((lane >> 4) & 1) << 5) | (((lane >> 5) & 1) << 8); }
; __device__ __forceinline__ void mla_block(const MlaRef& cur, char* lds) {
;     ...
;     const int tid = tid_, wid = __builtin_amdgcn_readfirstlane(tid >> 6), lane = tid & 63, r32 = lane & 31, hi = lane >> 5;
;     const int NT = (cur.P0 + QB) / KVBLK;
;     const int qlo = cur.P0 + wid * QBLK, qm = qlo + r32 - 4 * hi;
;     char* V_lds = lds; char* K_lds = lds + 2 * SHM_V; char* KR_lds = lds + 2 * SHM_V + 2 * SHM_K;
;     float* ws = (float*)(lds + 2 * SHM_V + 2 * SHM_K + 2 * SHM_KR) + wid * 64; float* li_l = ws, * al_l = ws + 32;
;     float m_reg = -1e30f, l_reg = 0; f32x16 o[4] = {};
;     const int sr = tid >> 4, sc = (tid & 15) * 8, vst0 = v_st(sr, sc), vst1 = v_st(32 + sr, sc), kws = KSWZ(sr, sc * 2), krws = (tid >> 3) * 144 + (tid & 7) * 16;
;     const int vb0 = (int)(uintptr_t)V_lds + v_rd_base(lane);
.LBB0_831:
	v_readlane_b32 s86, v246, 6
	v_readlane_b32 s60, v246, 8
	s_cmpk_gt_i32 s2, 0x1ff
	v_readlane_b32 s87, v246, 7
	v_readlane_b32 s85, v246, 10
	v_readlane_b32 s61, v246, 9
	s_cbranch_scc1 .LBB0_980
	s_movk_i32 s36, 0x180
	s_movk_i32 s37, 0xffe0
	s_movk_i32 s38, 0xf0
	s_movk_i32 s39, 0x90
	v_mov_b32_e32 v1, 0
	s_mov_b32 s40, 0x2e000000
	s_add_i32 s41, 0, 0x10000
	s_movk_i32 s42, 0x60
	s_mov_b64 s[8:9], 0x2e002000
	s_brev_b32 s43, -3
	s_mov_b32 s44, 0x41000000
	s_mov_b64 s[10:11], 0x2000
	v_mbcnt_hi_u32_b32 v167, -1, v180
	s_mov_b64 s[12:13], 0x34000000
	v_mov_b32_e32 v174, 0xff800000
	s_branch .LBB0_834

; __device__ __forceinline__ void load8(const bf16_t* src, float* v) { const u32x4 w = *(const u32x4*)src; v[0] = bf_lo(w.x); v[1] = bf_hi(w.x); v[2] = bf_lo(w.y); v[3] = bf_hi(w.y); v[4] = bf_lo(w.z); v[5] = bf_hi(w.z); v[6] = bf_lo(w.w); v[7] = bf_hi(w.w); }
; __device__ __forceinline__ int v_st(int k, int c) { const int kk = (k & ~0xC) | ((k & 4) << 1) | ((k & 8) >> 1); return ((kk >> 3) * 4 + (c >> 5)) * 512 + ((kk & 7) * 32 + (c & 31)) * 2; }
; __device__ __forceinline__ int v_rd_base(int lane) { return ((lane & 3) << 3) | (((lane >> 2) & 3) << 6) | (((lane >> 4) & 1) << 5) | (((lane >> 5) & 1) << 8); }
; #define VMW() asm volatile("s_waitcnt vmcnt(0)" ::: "memory")
; #define MSLOAD(R_, k0) do { st_v0 = load8<bf16>(MROW((R_).V, k0, sr)); st_v1 = load8<bf16>(MROW((R_).V, k0, 32 + sr));              \
;                          st_k0 = load8<bf16>(MROW((R_).K, k0, sr)); st_k1 = load8<bf16>(MROW((R_).K, k0, 32 + sr));                \
;                          st_kr = load8<bf16>((R_).KR + (size_t)((k0) + (tid >> 3)) * 64 + (tid & 7) * 8); } while (0)
; __device__ __forceinline__ void mla_block(const MlaRef& cur, char* lds) {
;     ...
;     const int tid = tid_, wid = __builtin_amdgcn_readfirstlane(tid >> 6), lane = tid & 63, r32 = lane & 31, hi = lane >> 5;
;     const int NT = (cur.P0 + QB) / KVBLK;
;     const int qlo = cur.P0 + wid * QBLK, qm = qlo + r32 - 4 * hi;
;     char* V_lds = lds; char* K_lds = lds + 2 * SHM_V; char* KR_lds = lds + 2 * SHM_V + 2 * SHM_K;
;     float* ws = (float*)(lds + 2 * SHM_V + 2 * SHM_K + 2 * SHM_KR) + wid * 64; float* li_l = ws, * al_l = ws + 32;
;     float m_reg = -1e30f, l_reg = 0; f32x16 o[4] = {};
;     const int sr = tid >> 4, sc = (tid & 15) * 8, vst0 = v_st(sr, sc), vst1 = v_st(32 + sr, sc), kws = KSWZ(sr, sc * 2), krws = (tid >> 3) * 144 + (tid & 7) * 16;
;     const int vb0 = (int)(uintptr_t)V_lds + v_rd_base(lane);
;     bf16x8 qr[12]; bf16x8 st_v0, st_v1, st_k0, st_k1, st_kr;
; #pragma unroll
;     for (int d0 = 0; d0 < 12; ++d0) qr[d0] = load8<bf16>(cur.Q + (size_t)(wid * QBLK + r32) * 192 + d0 * 16 + hi * 8);
;     MSLOAD(cur, 0); VMW(); MSWRITE(0);
.LBB0_836:
	s_mov_b64 s[6:7], s[0:1]
	s_xor_b64 s[22:23], s[4:5], -1
	s_load_dwordx2 s[6:7], s[6:7], 0xa8
	s_and_b64 s[4:5], s[4:5], exec
	s_cselect_b32 s25, s46, s45
	s_or_b32 s4, s14, s25
	s_mul_i32 s5, s4, 0x180
	s_mul_hi_u32 s4, s4, 0x180
	s_add_i32 s4, s4, s15
	s_waitcnt lgkmcnt(0)
	s_add_u32 s5, s6, s5
	s_addc_u32 s6, s7, s4
	s_add_u32 s4, s5, 0x20000000
	s_addc_u32 s5, s6, 0
	s_mov_b64 s[6:7], s[0:1]
	s_load_dwordx2 s[6:7], s[6:7], 0xa8
	s_mov_b64 s[26:27], s[0:1]
	s_load_dwordx2 s[30:31], s[26:27], 0xa8
	s_mov_b64 s[26:27], s[0:1]
	s_load_dwordx2 s[28:29], s[26:27], 0xa8
	s_waitcnt lgkmcnt(0)
	s_add_u32 s24, s6, s20
	s_addc_u32 s26, s7, s21
	s_add_u32 s34, s24, 0x26000000
	s_addc_u32 s35, s26, 0
	s_add_u32 s24, s28, s20
	s_addc_u32 s26, s29, s21
	s_add_u32 s50, s24, 0x2a000000
	s_addc_u32 s51, s26, 0
	s_mov_b64 s[26:27], s[0:1]
	v_mov_b32_e32 v175, v178
	s_load_dwordx2 s[26:27], s[26:27], 0xa8
	v_mov_b32_e32 v5, v1
	v_ashrrev_i32_e32 v2, 4, v175
	v_readfirstlane_b32 s49, v175
	v_lshlrev_b32_e32 v18, 3, v175
	v_add_u32_e32 v6, 32, v2
	v_ashrrev_i32_e32 v3, 31, v2
	s_ashr_i32 s52, s49, 1
	s_and_b32 s49, s49, 0x3fffffc0
	v_and_b32_e32 v0, 0x78, v18
	v_lshlrev_b64 v[10:11], 8, v[2:3]
	v_ashrrev_i32_e32 v7, 31, v6
	s_lshl_b32 s49, s49, 2
	v_lshlrev_b32_e32 v4, 1, v0
	v_lshl_add_u64 v[12:13], s[50:51], 0, v[10:11]
	v_lshlrev_b64 v[14:15], 8, v[6:7]
	s_and_b32 s24, s52, 0xffffffe0
	s_add_i32 s49, s49, 0
	s_add_i32 s54, s25, 0x100
	v_lshl_add_u64 v[12:13], v[12:13], 0, v[4:5]
	v_lshl_add_u64 v[16:17], s[50:51], 0, v[14:15]
	s_add_i32 s33, s24, s25
	s_add_i32 s53, s49, 0x14800
	v_ashrrev_i32_e32 v8, 3, v175
	s_lshr_b32 s49, s54, 6
	v_lshl_add_u64 v[16:17], v[16:17], 0, v[4:5]
	global_load_dwordx4 v[98:101], v[12:13], off
	global_load_dwordx4 v[102:105], v[16:17], off
	v_lshl_add_u64 v[12:13], s[34:35], 0, v[10:11]
	v_lshl_add_u64 v[12:13], v[12:13], 0, v[4:5]
	v_lshl_add_u64 v[14:15], s[34:35], 0, v[14:15]
	v_ashrrev_i32_e32 v9, 31, v8
	s_add_u32 s30, s30, s16
	v_lshl_add_u64 v[14:15], v[14:15], 0, v[4:5]
	global_load_dwordx4 v[106:109], v[12:13], off
	global_load_dwordx4 v[110:113], v[14:15], off
	v_lshlrev_b64 v[12:13], 7, v[8:9]
	s_addc_u32 s31, s31, s17
	v_lshlrev_b32_e32 v3, 4, v175
	v_lshl_add_u64 v[14:15], s[30:31], 0, v[12:13]
	v_and_b32_e32 v16, 0x70, v3
	v_mov_b32_e32 v17, v1
	v_and_b32_e32 v0, 0xfffff0, v2
	v_lshlrev_b32_e32 v7, 1, v2
	v_lshl_add_u64 v[14:15], v[14:15], 0, v[16:17]
	v_and_or_b32 v0, v7, 8, v0
	v_add_co_u32_e32 v14, vcc, s40, v14
	v_lshrrev_b32_e32 v0, 1, v0
	v_bfe_u32 v9, v18, 5, 2
	v_addc_co_u32_e32 v15, vcc, 0, v15, vcc
	v_or_b32_e32 v0, v0, v9
	global_load_dwordx4 v[130:133], v[14:15], off
	v_lshrrev_b32_e32 v7, 1, v2
	v_lshlrev_b32_e32 v14, 9, v0
	v_and_b32_e32 v0, 3, v2
	v_and_or_b32 v0, v7, 4, v0
	v_lshlrev_b32_e32 v15, 6, v0
	v_mov_b32_e32 v0, s52
	v_bfe_u32 v176, v175, 5, 1
	v_and_b32_e32 v19, 0xfffff0, v6
	v_lshlrev_b32_e32 v20, 1, v6
	v_bfi_b32 v0, s37, v0, v175
	v_mov_b64_e32 v[6:7], s[4:5]
	v_mad_i64_i32 v[6:7], s[4:5], v0, s36, v[6:7]
	v_lshlrev_b32_e32 v0, 4, v176
	v_lshl_add_u64 v[6:7], v[6:7], 0, v[0:1]
	global_load_dwordx4 v[114:117], v[6:7], off
	global_load_dwordx4 v[118:121], v[6:7], off offset:32
	global_load_dwordx4 v[122:125], v[6:7], off offset:64
	global_load_dwordx4 v[126:129], v[6:7], off offset:96
	global_load_dwordx4 v[134:137], v[6:7], off offset:128
	global_load_dwordx4 v[138:141], v[6:7], off offset:160
	global_load_dwordx4 v[142:145], v[6:7], off offset:192
	global_load_dwordx4 v[146:149], v[6:7], off offset:224
	global_load_dwordx4 v[150:153], v[6:7], off offset:256
	global_load_dwordx4 v[154:157], v[6:7], off offset:288
	global_load_dwordx4 v[158:161], v[6:7], off offset:320
	global_load_dwordx4 v[162:165], v[6:7], off offset:352
	v_and_or_b32 v6, v20, 8, v19
	v_lshrrev_b32_e32 v6, 1, v6
	v_or_b32_e32 v6, v6, v9
	v_and_b32_e32 v17, 48, v4
	v_lshlrev_b32_e32 v6, 9, v6
	v_and_b32_e32 v177, 31, v175
	v_or3_b32 v181, v6, v15, v17
	v_bitop3_b32 v4, v4, v175, s38 bitop3:0x78
	v_mul_lo_u32 v6, v8, s39
	v_lshlrev_b32_e32 v2, 8, v2
	s_or_b32 s52, s33, 31
	v_add3_u32 v184, 0, v4, v2
	v_add3_u32 v185, s41, v6, v16
	v_lshlrev_b32_e32 v2, 1, v175
	v_and_b32_e32 v4, 0xc0, v3
	v_and_b32_e32 v6, 0x118, v18
	v_bitop3_b32 v188, v0, v3, s38 bitop3:0x78
	v_and_b32_e32 v234, 0xf0, v3
	v_mul_u32_u24_e32 v3, 0x90, v177
	s_cmp_lg_u32 0, -1
	v_bitop3_b32 v189, v0, v234, 32 bitop3:0x36
	v_bitop3_b32 v190, v0, v234, 64 bitop3:0x36
	v_bitop3_b32 v191, v0, v234, s42 bitop3:0x36
	v_add3_u32 v192, s41, v3, v0
	v_add_u32_e32 v183, s53, v0
	v_and_or_b32 v0, v2, 32, v6
	s_cselect_b32 s34, 0, 0
	v_add3_u32 v193, v4, s34, v0
	s_lshl_b32 s34, s54, 8
	v_lshl_add_u32 v187, v177, 2, s53
	s_and_b32 s53, s34, 0x3fc000
	s_add_i32 s34, s33, 0xbfffffc5
	s_add_u32 s28, s28, s18
	v_lshlrev_b32_e32 v7, 2, v176
	v_or3_b32 v182, v14, v15, v17
	v_add_u32_e32 v0, s34, v177
	s_addc_u32 s29, s29, s19
	v_add_u32_e32 v8, 0, v182
	v_sub_u32_e32 v194, v0, v7
	v_or_b32_e32 v12, v12, v16
	v_and_b32_e32 v0, 15, v175
	s_add_u32 s6, s6, s18
	v_and_b32_e32 v5, 63, v175
	s_waitcnt vmcnt(0)
; __device__ __forceinline__ void load8(const bf16_t* src, float* v) { const u32x4 w = *(const u32x4*)src; v[0] = bf_lo(w.x); v[1] = bf_hi(w.x); v[2] = bf_lo(w.y); v[3] = bf_hi(w.y); v[4] = bf_lo(w.z); v[5] = bf_hi(w.z); v[6] = bf_lo(w.w); v[7] = bf_hi(w.w); }
; __device__ __forceinline__ int v_st(int k, int c) { const int kk = (k & ~0xC) | ((k & 4) << 1) | ((k & 8) >> 1); return ((kk >> 3) * 4 + (c >> 5)) * 512 + ((kk & 7) * 32 + (c & 31)) * 2; }
; __device__ __forceinline__ int v_rd_base(int lane) { return ((lane & 3) << 3) | (((lane >> 2) & 3) << 6) | (((lane >> 4) & 1) << 5) | (((lane >> 5) & 1) << 8); }
; #define VMW() asm volatile("s_waitcnt vmcnt(0)" ::: "memory")
; #define MSLOAD(R_, k0) do { st_v0 = load8<bf16>(MROW((R_).V, k0, sr)); st_v1 = load8<bf16>(MROW((R_).V, k0, 32 + sr));              \
;                          st_k0 = load8<bf16>(MROW((R_).K, k0, sr)); st_k1 = load8<bf16>(MROW((R_).K, k0, 32 + sr));                \
;                          st_kr = load8<bf16>((R_).KR + (size_t)((k0) + (tid >> 3)) * 64 + (tid & 7) * 8); } while (0)
; #define MSWRITE(bf) do { *(bf16x8*)(V_lds + (bf) * SHM_V + vst0) = st_v0; *(bf16x8*)(V_lds + (bf) * SHM_V + vst1) = st_v1;               \
;                          *(bf16x8*)(K_lds + (bf) * SHM_K + kws) = st_k0; *(bf16x8*)(K_lds + (bf) * SHM_K + kws + 32 * 256) = st_k1;       \
;                          *(bf16x8*)(KR_lds + (bf) * SHM_KR + krws) = st_kr; } while (0)
; __device__ __forceinline__ void mla_block(const MlaRef& cur, char* lds) {
;     ...
;     float m_reg = -1e30f, l_reg = 0; f32x16 o[4] = {};
;     const int sr = tid >> 4, sc = (tid & 15) * 8, vst0 = v_st(sr, sc), vst1 = v_st(32 + sr, sc), kws = KSWZ(sr, sc * 2), krws = (tid >> 3) * 144 + (tid & 7) * 16;
;     const int vb0 = (int)(uintptr_t)V_lds + v_rd_base(lane);
;     bf16x8 qr[12]; bf16x8 st_v0, st_v1, st_k0, st_k1, st_kr;
; #pragma unroll
;     for (int d0 = 0; d0 < 12; ++d0) qr[d0] = load8<bf16>(cur.Q + (size_t)(wid * QBLK + r32) * 192 + d0 * 16 + hi * 8);
;     MSLOAD(cur, 0); VMW(); MSWRITE(0);
;     __syncthreads();
	s_waitcnt vmcnt(16)
	ds_write_b128 v8, v[98:101]
	v_add_u32_e32 v8, 0, v181
	v_lshl_add_u64 v[2:3], s[30:31], 0, v[12:13]
	v_lshl_or_b32 v10, v0, 4, v10
	s_addc_u32 s7, s7, s19
	v_mov_b32_e32 v14, v1
	v_mov_b32_e32 v15, v1
	s_waitcnt vmcnt(15)
	ds_write_b128 v8, v[102:105]
	v_cmp_gt_u32_e64 s[4:5], 32, v5
	v_lshl_add_u64 v[168:169], v[2:3], 0, s[8:9]
	v_lshl_add_u64 v[170:171], s[28:29], 0, v[10:11]
	v_lshl_add_u64 v[172:173], s[6:7], 0, v[10:11]
	v_mov_b32_e32 v0, v1
	v_mov_b32_e32 v2, v1
	v_mov_b32_e32 v3, v1
	v_mov_b32_e32 v4, v1
	v_mov_b32_e32 v5, v1
	v_mov_b32_e32 v6, v1
	v_mov_b32_e32 v7, v1
	v_mov_b32_e32 v8, v1
	v_mov_b32_e32 v9, v1
	v_mov_b32_e32 v10, v1
	v_mov_b32_e32 v11, v1
	v_mov_b32_e32 v12, v1
	v_mov_b32_e32 v13, v1
	v_mov_b64_e32 v[64:65], v[14:15]
	v_mov_b64_e32 v[48:49], v[14:15]
	v_mov_b64_e32 v[32:33], v[14:15]
	v_mov_b64_e32 v[62:63], v[12:13]
	v_mov_b64_e32 v[60:61], v[10:11]
	v_mov_b64_e32 v[58:59], v[8:9]
	v_mov_b64_e32 v[56:57], v[6:7]
	v_mov_b64_e32 v[54:55], v[4:5]
	v_mov_b64_e32 v[52:53], v[2:3]
	v_mov_b64_e32 v[50:51], v[0:1]
	v_mov_b64_e32 v[46:47], v[12:13]
	v_mov_b64_e32 v[44:45], v[10:11]
	v_mov_b64_e32 v[42:43], v[8:9]
	v_mov_b64_e32 v[40:41], v[6:7]
	v_mov_b64_e32 v[38:39], v[4:5]
	v_mov_b64_e32 v[36:37], v[2:3]
	v_mov_b64_e32 v[34:35], v[0:1]
	v_mov_b64_e32 v[30:31], v[12:13]
	v_mov_b64_e32 v[28:29], v[10:11]
	v_mov_b64_e32 v[26:27], v[8:9]
	v_mov_b64_e32 v[24:25], v[6:7]
	v_mov_b64_e32 v[22:23], v[4:5]
	v_mov_b64_e32 v[20:21], v[2:3]
	v_mov_b64_e32 v[18:19], v[0:1]
	v_mov_b64_e32 v[16:17], v[14:15]
	s_mov_b32 s50, 1
	s_mov_b32 s51, 63
	v_lshlrev_b32_e32 v186, 8, v177
	v_mov_b32_e32 v196, 0
	v_mov_b32_e32 v195, 0xf149f2ca
	s_mov_b64 s[28:29], 0
	v_mov_b64_e32 v[14:15], v[12:13]
	v_mov_b64_e32 v[12:13], v[10:11]
	v_mov_b64_e32 v[10:11], v[8:9]
	v_mov_b64_e32 v[8:9], v[6:7]
	v_mov_b64_e32 v[6:7], v[4:5]
	v_mov_b64_e32 v[4:5], v[2:3]
	v_mov_b64_e32 v[2:3], v[0:1]
	s_waitcnt vmcnt(14)
	ds_write_b128 v184, v[106:109] offset:32768
	s_waitcnt vmcnt(13)
	ds_write_b128 v184, v[110:113] offset:40960
	s_waitcnt vmcnt(12)
	ds_write_b128 v185, v[130:133]
	s_waitcnt vmcnt(0) lgkmcnt(0)
	s_barrier
	s_branch .LBB0_838

; __device__ __forceinline__ void mask_tile(f32x16& p0, f32x16& p1, int dq, unsigned W) {
;     const float NEG = -__builtin_inff();
; #pragma unroll
;     for (int r = 0; r < 16; ++r) {
;         const int c = (r & 3) + 8 * (r >> 2);
;         if ((unsigned)(dq - c) >= W) p0[r] = NEG;
;         if ((unsigned)(dq - c - 32) >= W) p1[r] = NEG;
;     }
; }
; template <int KB>
; __device__ __forceinline__ void qkt_mla(f32x16& p0, f32x16& p1, const char* K_lds, const char* KR_lds, int r32, int hi, const bf16x8* qr) {
;     p0 = f32x16{}; p1 = f32x16{};
;     const char* kb[4];
; #pragma unroll
;     for (int dd = 0; dd < 4; ++dd) kb[dd] = K_lds + KB * SHM_K + KSWZ(r32, (dd * 16 + hi * 8) * 2);
; #pragma unroll
;     for (int d0 = 0; d0 < 8; ++d0) { const char* a = kb[d0 & 3] + (d0 >> 2) * 128;
;         bf16x8 b0 = *reinterpret_cast<const bf16x8*>(a);
;         bf16x8 b1 = *reinterpret_cast<const bf16x8*>(a + 32 * 256);
;         p0 = __builtin_amdgcn_mfma_f32_32x32x16_bf16(b0, qr[d0], p0, 0, 0, 0);
;         p1 = __builtin_amdgcn_mfma_f32_32x32x16_bf16(b1, qr[d0], p1, 0, 0, 0); }
;     const char* kr = KR_lds + KB * SHM_KR + r32 * 144 + hi * 16;
; #pragma unroll
;     for (int d0 = 0; d0 < 4; ++d0) {
;         bf16x8 b0 = *reinterpret_cast<const bf16x8*>(kr + d0 * 32);
;         bf16x8 b1 = *reinterpret_cast<const bf16x8*>(kr + d0 * 32 + 32 * 144);
;         p0 = __builtin_amdgcn_mfma_f32_32x32x16_bf16(b0, qr[8 + d0], p0, 0, 0, 0);
;         p1 = __builtin_amdgcn_mfma_f32_32x32x16_bf16(b1, qr[8 + d0], p1, 0, 0, 0); }
; }
.LBB0_840:
	s_add_i32 s6, s50, -1
	s_and_b32 s54, s6, 1
	s_sub_i32 s6, s51, 63
	s_cmp_gt_i32 s6, s52
	s_cbranch_scc1 .LBB0_848
	s_lshl_b32 s55, s54, 14
	s_add_i32 s6, s55, 0
	v_add3_u32 v0, s6, v188, v186
	v_xor_b32_e32 v234, 0x80, v0
	ds_read_b128 v[66:69], v0 offset:32768
	ds_read_b128 v[198:201], v234 offset:32768
	v_add3_u32 v197, s6, v189, v186
	v_xor_b32_e32 v235, 0x80, v197
	s_cmp_le_i32 s51, s33
	s_waitcnt lgkmcnt(1)
	v_mfma_f32_32x32x16_bf16 v[82:97], v[66:69], v[114:117], 0
	ds_read_b128 v[66:69], v0 offset:40960
	ds_read_b128 v[202:205], v234 offset:40960
	ds_read_b128 v[206:209], v197 offset:32768
	ds_read_b128 v[210:213], v235 offset:32768
	v_add3_u32 v0, s6, v190, v186
	v_xor_b32_e32 v234, 0x80, v0
	ds_read_b128 v[214:217], v235 offset:40960
	s_waitcnt lgkmcnt(2)
	v_mfma_f32_32x32x16_bf16 v[82:97], v[206:209], v[118:121], v[82:97]
	ds_read_b128 v[206:209], v197 offset:40960
	v_add3_u32 v197, s6, v191, v186
	v_xor_b32_e32 v235, 0x80, v197
	s_mul_i32 s6, s54, 0x2400
	v_mfma_f32_32x32x16_bf16 v[66:81], v[66:69], v[114:117], 0
	s_waitcnt lgkmcnt(0)
	v_mfma_f32_32x32x16_bf16 v[66:81], v[206:209], v[118:121], v[66:81]
	ds_read_b128 v[206:209], v0 offset:32768
	ds_read_b128 v[218:221], v234 offset:32768
	ds_read_b128 v[222:225], v234 offset:40960
	s_waitcnt lgkmcnt(2)
	v_mfma_f32_32x32x16_bf16 v[82:97], v[206:209], v[122:125], v[82:97]
	ds_read_b128 v[206:209], v0 offset:40960
	v_add_u32_e32 v0, s6, v192
	s_waitcnt lgkmcnt(0)
	v_mfma_f32_32x32x16_bf16 v[66:81], v[206:209], v[122:125], v[66:81]
	ds_read_b128 v[206:209], v197 offset:32768
	ds_read_b128 v[226:229], v235 offset:32768
	s_waitcnt lgkmcnt(1)
	v_mfma_f32_32x32x16_bf16 v[82:97], v[206:209], v[126:129], v[82:97]
	ds_read_b128 v[206:209], v197 offset:40960
	ds_read_b128 v[230:233], v235 offset:40960
	s_waitcnt lgkmcnt(1)
	v_mfma_f32_32x32x16_bf16 v[66:81], v[206:209], v[126:129], v[66:81]
	v_mfma_f32_32x32x16_bf16 v[82:97], v[198:201], v[134:137], v[82:97]
	v_mfma_f32_32x32x16_bf16 v[66:81], v[202:205], v[134:137], v[66:81]
	ds_read_b128 v[198:201], v0
	ds_read_b128 v[202:205], v0 offset:32
	v_mfma_f32_32x32x16_bf16 v[82:97], v[210:213], v[138:141], v[82:97]
	v_mfma_f32_32x32x16_bf16 v[66:81], v[214:217], v[138:141], v[66:81]
	v_mfma_f32_32x32x16_bf16 v[82:97], v[218:221], v[142:145], v[82:97]
	v_mfma_f32_32x32x16_bf16 v[66:81], v[222:225], v[142:145], v[66:81]
	v_mfma_f32_32x32x16_bf16 v[82:97], v[226:229], v[146:149], v[82:97]
	s_waitcnt lgkmcnt(2)
	v_mfma_f32_32x32x16_bf16 v[66:81], v[230:233], v[146:149], v[66:81]
	s_waitcnt lgkmcnt(1)
	v_mfma_f32_32x32x16_bf16 v[82:97], v[198:201], v[150:153], v[82:97]
	ds_read_b128 v[198:201], v0 offset:4608
	ds_read_b128 v[206:209], v0 offset:4640
	s_waitcnt lgkmcnt(1)
	v_mfma_f32_32x32x16_bf16 v[66:81], v[198:201], v[150:153], v[66:81]
	v_mfma_f32_32x32x16_bf16 v[82:97], v[202:205], v[154:157], v[82:97]
	ds_read_b128 v[198:201], v0 offset:64
	ds_read_b128 v[202:205], v0 offset:96
	s_waitcnt lgkmcnt(2)
	v_mfma_f32_32x32x16_bf16 v[66:81], v[206:209], v[154:157], v[66:81]
	s_waitcnt lgkmcnt(1)
	v_mfma_f32_32x32x16_bf16 v[82:97], v[198:201], v[158:161], v[82:97]
	ds_read_b128 v[198:201], v0 offset:4672
	ds_read_b128 v[206:209], v0 offset:4704
	s_waitcnt lgkmcnt(1)
	v_mfma_f32_32x32x16_bf16 v[66:81], v[198:201], v[158:161], v[66:81]
	v_mfma_f32_32x32x16_bf16 v[82:97], v[202:205], v[162:165], v[82:97]
	s_waitcnt lgkmcnt(0)
	v_mfma_f32_32x32x16_bf16 v[66:81], v[206:209], v[162:165], v[66:81]
	s_cbranch_scc1 .LBB0_843
	v_add_u32_e32 v0, 0x4000003b, v194
	v_cmp_gt_u32_e32 vcc, 2.0, v0
	v_add_u32_e32 v0, 27, v194
	s_nop 5
	v_cndmask_b32_e32 v82, v174, v82, vcc
	v_cmp_lt_u32_e32 vcc, s43, v0
	v_add_u32_e32 v0, 58, v194
	s_nop 0
	v_cndmask_b32_e32 v66, v174, v66, vcc
	v_cmp_lt_u32_e32 vcc, s43, v0
	v_add_u32_e32 v0, 26, v194
	s_nop 0
	v_cndmask_b32_e32 v83, v174, v83, vcc
	v_cmp_lt_u32_e32 vcc, s43, v0
	v_add_u32_e32 v0, 57, v194
	s_nop 0
	v_cndmask_b32_e32 v67, v174, v67, vcc
	v_cmp_lt_u32_e32 vcc, s43, v0
	v_add_u32_e32 v0, 25, v194
	s_nop 0
	v_cndmask_b32_e32 v84, v174, v84, vcc
	v_cmp_lt_u32_e32 vcc, s43, v0
	v_add_u32_e32 v0, 56, v194
	s_nop 0
	v_cndmask_b32_e32 v68, v174, v68, vcc
	v_cmp_lt_u32_e32 vcc, s43, v0
	v_add_u32_e32 v0, 24, v194
	s_nop 0
	v_cndmask_b32_e32 v85, v174, v85, vcc
	v_cmp_lt_u32_e32 vcc, s43, v0
	v_add_u32_e32 v0, 51, v194
	s_nop 0
	v_cndmask_b32_e32 v69, v174, v69, vcc
	v_cmp_lt_u32_e32 vcc, s43, v0
	v_add_u32_e32 v0, 19, v194
	s_nop 0
	v_cndmask_b32_e32 v86, v174, v86, vcc
	v_cmp_lt_u32_e32 vcc, s43, v0
	v_add_u32_e32 v0, 50, v194
	s_nop 0
	v_cndmask_b32_e32 v70, v174, v70, vcc
	v_cmp_lt_u32_e32 vcc, s43, v0
	v_add_u32_e32 v0, 18, v194
	s_nop 0
	v_cndmask_b32_e32 v87, v174, v87, vcc
	v_cmp_lt_u32_e32 vcc, s43, v0
	v_add_u32_e32 v0, 49, v194
	s_nop 0
	v_cndmask_b32_e32 v71, v174, v71, vcc
	v_cmp_lt_u32_e32 vcc, s43, v0
	v_add_u32_e32 v0, 17, v194
	s_nop 0
	v_cndmask_b32_e32 v88, v174, v88, vcc
	v_cmp_lt_u32_e32 vcc, s43, v0
	v_add_u32_e32 v0, 48, v194
	s_nop 0
	v_cndmask_b32_e32 v72, v174, v72, vcc
	v_cmp_lt_u32_e32 vcc, s43, v0
	v_add_u32_e32 v0, 16, v194
	s_nop 0
	v_cndmask_b32_e32 v89, v174, v89, vcc
	v_cmp_lt_u32_e32 vcc, s43, v0
	v_add_u32_e32 v0, 43, v194
	s_nop 0
	v_cndmask_b32_e32 v73, v174, v73, vcc
	v_cmp_lt_u32_e32 vcc, s43, v0
	v_add_u32_e32 v0, 11, v194
	s_nop 0
	v_cndmask_b32_e32 v90, v174, v90, vcc
	v_cmp_lt_u32_e32 vcc, s43, v0
	v_add_u32_e32 v0, 42, v194
	s_nop 0
	v_cndmask_b32_e32 v74, v174, v74, vcc
	v_cmp_lt_u32_e32 vcc, s43, v0
	v_add_u32_e32 v0, 10, v194
	s_nop 0
	v_cndmask_b32_e32 v91, v174, v91, vcc
	v_cmp_lt_u32_e32 vcc, s43, v0
	v_add_u32_e32 v0, 41, v194
	s_nop 0
	v_cndmask_b32_e32 v75, v174, v75, vcc
	v_cmp_lt_u32_e32 vcc, s43, v0
	v_add_u32_e32 v0, 9, v194
	s_nop 0
	v_cndmask_b32_e32 v92, v174, v92, vcc
	v_cmp_lt_u32_e32 vcc, s43, v0
	v_add_u32_e32 v0, 40, v194
	s_nop 0
	v_cndmask_b32_e32 v76, v174, v76, vcc
	v_cmp_lt_u32_e32 vcc, s43, v0
	v_add_u32_e32 v0, 8, v194
	s_nop 0
	v_cndmask_b32_e32 v93, v174, v93, vcc
	v_cmp_lt_u32_e32 vcc, s43, v0
	v_add_u32_e32 v0, 35, v194
	s_nop 0
	v_cndmask_b32_e32 v77, v174, v77, vcc
	v_cmp_lt_u32_e32 vcc, s43, v0
	v_add_u32_e32 v0, 3, v194
	s_nop 0
	v_cndmask_b32_e32 v94, v174, v94, vcc
	v_cmp_lt_u32_e32 vcc, s43, v0
	v_add_u32_e32 v0, 34, v194
	s_nop 0
	v_cndmask_b32_e32 v78, v174, v78, vcc
	v_cmp_lt_u32_e32 vcc, s43, v0
	v_add_u32_e32 v0, 2, v194
	s_nop 0
	v_cndmask_b32_e32 v95, v174, v95, vcc
	v_cmp_lt_u32_e32 vcc, s43, v0
	v_add_u32_e32 v0, 33, v194
	s_nop 0
	v_cndmask_b32_e32 v79, v174, v79, vcc
	v_cmp_lt_u32_e32 vcc, s43, v0
	v_add_u32_e32 v0, 1, v194
	s_nop 0
	v_cndmask_b32_e32 v96, v174, v96, vcc
	v_cmp_lt_u32_e32 vcc, s43, v0
	v_add_u32_e32 v0, 32, v194
	s_nop 0
	v_cndmask_b32_e32 v80, v174, v80, vcc
	v_cmp_lt_u32_e32 vcc, s43, v0
	s_nop 1
	v_cndmask_b32_e32 v97, v174, v97, vcc
	v_cmp_lt_u32_e32 vcc, s43, v194
	s_nop 1
	v_cndmask_b32_e32 v81, v174, v81, vcc

; __device__ __forceinline__ void store8(bf16_t* dst, const float* v) { u32x4 w; w.x = pk2(v[0], v[1]); w.y = pk2(v[2], v[3]); w.z = pk2(v[4], v[5]); w.w = pk2(v[6], v[7]); *(u32x4*)dst = w; }
; __device__ __forceinline__ void load8(const bf16_t* src, float* v) { const u32x4 w = *(const u32x4*)src; v[0] = bf_lo(w.x); v[1] = bf_hi(w.x); v[2] = bf_lo(w.y); v[3] = bf_hi(w.y); v[4] = bf_lo(w.z); v[5] = bf_hi(w.z); v[6] = bf_lo(w.w); v[7] = bf_hi(w.w); }
;     __device__ __forceinline__ void operator()(const pg8::f32x4 (&acc)[2][2][4][2], const pg8::Unit& u, int wr, int wc, int fr, int fq) const {
;     ...
; #pragma unroll
;         for (int ai = 0; ai < 2; ++ai)
; #pragma unroll
;             for (int m = 0; m < 4; ++m) {
;                 const int row = u.pm * 256 + ai * 128 + wr * 64 + m * 16 + fr;
;                 const int bb = row >> 13, ss = row & 8191;
;                 float ssq = 0.f;
;                 float rs = 1.f;
;                 if constexpr (KIND == EK_Q || KIND == EK_KV) rs = __builtin_amdgcn_rsqf(a.ssq0[row] * (1.f / 512.f) + EPS);
;                 if constexpr (KIND == EK_FIN) rs = __builtin_amdgcn_rsqf(a.ssq0[row] * (1.f / 2048.f) + EPS);
; #pragma unroll
;                 for (int bj = 0; bj < 2; ++bj) {
;                     const int cl = bj * 128 + wc * 32 + fq * 8;
;                     float v[8];
; #pragma unroll
;                     for (int j = 0; j < 4; ++j) { v[j] = acc[ai][bj][m][0][j]; v[4 + j] = acc[ai][bj][m][1][j]; }
;     ...
;                     } else if constexpr (KIND == EK_MIX1) {
;                         const size_t off = (size_t)row * 2048 + pn * 256 + cl; float g[8]; load8(a.g0 + off, g);
; #pragma unroll
;                         for (int j = 0; j < 8; ++j) v[j] *= g[j];
;                         store8(a.o0 + off, v);
.LBB0_1052:
	v_lshl_add_u32 v148, s26, 8, v137
	s_lshl_b32 s26, s27, 9
	v_lshlrev_b32_e32 v148, 12, v148
	v_lshl_add_u32 v149, v136, 1, s26
	v_add_u32_e32 v148, v148, v149
	global_load_dwordx4 v[154:157], v148, s[8:9]
	global_load_dwordx4 v[158:161], v148, s[8:9] offset:256
	v_add_u32_e32 v149, 0x10000, v148
	global_load_dwordx4 v[162:165], v149, s[8:9]
	global_load_dwordx4 v[168:171], v149, s[8:9] offset:256
	v_add_u32_e32 v149, 0x20000, v148
	global_load_dwordx4 v[182:185], v149, s[8:9]
	global_load_dwordx4 v[186:189], v149, s[8:9] offset:256
	v_add_u32_e32 v149, 0x30000, v148
	global_load_dwordx4 v[190:193], v149, s[8:9]
	global_load_dwordx4 v[194:197], v149, s[8:9] offset:256
	v_add_u32_e32 v149, 0x80000, v148
	global_load_dwordx4 v[198:201], v149, s[8:9]
	global_load_dwordx4 v[202:205], v149, s[8:9] offset:256
	v_add_u32_e32 v149, 0x90000, v148
	global_load_dwordx4 v[206:209], v149, s[8:9]
	global_load_dwordx4 v[210:213], v149, s[8:9] offset:256
	v_add_u32_e32 v149, 0xa0000, v148
	global_load_dwordx4 v[214:217], v149, s[8:9]
	global_load_dwordx4 v[218:221], v149, s[8:9] offset:256
	v_add_u32_e32 v149, 0xb0000, v148
	global_load_dwordx4 v[222:225], v149, s[8:9]
	global_load_dwordx4 v[226:229], v149, s[8:9] offset:256
	s_waitcnt vmcnt(15)
	v_lshlrev_b32_e32 v230, 16, v154
	v_and_b32_e32 v154, 0xffff0000, v154
	v_lshlrev_b32_e32 v231, 16, v155
	v_and_b32_e32 v155, 0xffff0000, v155
	v_lshlrev_b32_e32 v232, 16, v156
	v_and_b32_e32 v156, 0xffff0000, v156
	v_lshlrev_b32_e32 v233, 16, v157
	v_and_b32_e32 v157, 0xffff0000, v157
	v_mul_f32_e32 v124, v124, v230
	v_mul_f32_e32 v125, v125, v154
	v_mul_f32_e32 v126, v126, v231
	v_mul_f32_e32 v127, v127, v155
	v_mul_f32_e32 v120, v120, v232
	v_mul_f32_e32 v121, v121, v156
	v_mul_f32_e32 v122, v122, v233
	v_mul_f32_e32 v123, v123, v157
	v_cvt_pk_bf16_f32 v124, v124, v125
	v_cvt_pk_bf16_f32 v125, v126, v127
	v_cvt_pk_bf16_f32 v126, v120, v121
	v_cvt_pk_bf16_f32 v127, v122, v123
	global_store_dwordx4 v148, v[124:127], s[12:13]
	s_waitcnt vmcnt(15)
	v_lshlrev_b32_e32 v230, 16, v158
	v_and_b32_e32 v158, 0xffff0000, v158
	v_lshlrev_b32_e32 v231, 16, v159
	v_and_b32_e32 v159, 0xffff0000, v159
	v_lshlrev_b32_e32 v232, 16, v160
	v_and_b32_e32 v160, 0xffff0000, v160
	v_lshlrev_b32_e32 v233, 16, v161
	v_and_b32_e32 v161, 0xffff0000, v161
	v_mul_f32_e32 v116, v116, v230
	v_mul_f32_e32 v117, v117, v158
	v_mul_f32_e32 v118, v118, v231
	v_mul_f32_e32 v119, v119, v159
	v_mul_f32_e32 v112, v112, v232
	v_mul_f32_e32 v113, v113, v160
	v_mul_f32_e32 v114, v114, v233
	v_mul_f32_e32 v115, v115, v161
	v_cvt_pk_bf16_f32 v116, v116, v117
	v_cvt_pk_bf16_f32 v117, v118, v119
	v_cvt_pk_bf16_f32 v118, v112, v113
	v_cvt_pk_bf16_f32 v119, v114, v115
	global_store_dwordx4 v148, v[116:119], s[12:13] offset:256
	s_waitcnt vmcnt(15)
	v_lshlrev_b32_e32 v230, 16, v162
	v_and_b32_e32 v162, 0xffff0000, v162
	v_lshlrev_b32_e32 v231, 16, v163
	v_and_b32_e32 v163, 0xffff0000, v163
	v_lshlrev_b32_e32 v232, 16, v164
	v_and_b32_e32 v164, 0xffff0000, v164
	v_lshlrev_b32_e32 v233, 16, v165
	v_and_b32_e32 v165, 0xffff0000, v165
	v_mul_f32_e32 v108, v108, v230
	v_mul_f32_e32 v109, v109, v162
	v_mul_f32_e32 v110, v110, v231
	v_mul_f32_e32 v111, v111, v163
	v_mul_f32_e32 v104, v104, v232
	v_mul_f32_e32 v105, v105, v164
	v_mul_f32_e32 v106, v106, v233
	v_mul_f32_e32 v107, v107, v165
	v_cvt_pk_bf16_f32 v108, v108, v109
	v_cvt_pk_bf16_f32 v109, v110, v111
	v_cvt_pk_bf16_f32 v110, v104, v105
	v_cvt_pk_bf16_f32 v111, v106, v107
	v_add_u32_e32 v149, 0x10000, v148
	global_store_dwordx4 v149, v[108:111], s[12:13]
	s_waitcnt vmcnt(15)
	v_lshlrev_b32_e32 v230, 16, v168
	v_and_b32_e32 v168, 0xffff0000, v168
	v_lshlrev_b32_e32 v231, 16, v169
	v_and_b32_e32 v169, 0xffff0000, v169
	v_lshlrev_b32_e32 v232, 16, v170
	v_and_b32_e32 v170, 0xffff0000, v170
	v_lshlrev_b32_e32 v233, 16, v171
	v_and_b32_e32 v171, 0xffff0000, v171
	v_mul_f32_e32 v100, v100, v230
	v_mul_f32_e32 v101, v101, v168
	v_mul_f32_e32 v102, v102, v231
	v_mul_f32_e32 v103, v103, v169
	v_mul_f32_e32 v96, v96, v232
	v_mul_f32_e32 v97, v97, v170
	v_mul_f32_e32 v98, v98, v233
	v_mul_f32_e32 v99, v99, v171
	v_cvt_pk_bf16_f32 v100, v100, v101
	v_cvt_pk_bf16_f32 v101, v102, v103
	v_cvt_pk_bf16_f32 v102, v96, v97
	v_cvt_pk_bf16_f32 v103, v98, v99
	global_store_dwordx4 v149, v[100:103], s[12:13] offset:256
	s_waitcnt vmcnt(15)
	v_lshlrev_b32_e32 v230, 16, v182
	v_and_b32_e32 v182, 0xffff0000, v182
	v_lshlrev_b32_e32 v231, 16, v183
	v_and_b32_e32 v183, 0xffff0000, v183
	v_lshlrev_b32_e32 v232, 16, v184
	v_and_b32_e32 v184, 0xffff0000, v184
	v_lshlrev_b32_e32 v233, 16, v185
	v_and_b32_e32 v185, 0xffff0000, v185
	v_mul_f32_e32 v92, v92, v230
	v_mul_f32_e32 v93, v93, v182
	v_mul_f32_e32 v94, v94, v231
	v_mul_f32_e32 v95, v95, v183
	v_mul_f32_e32 v88, v88, v232
	v_mul_f32_e32 v89, v89, v184
	v_mul_f32_e32 v90, v90, v233
	v_mul_f32_e32 v91, v91, v185
	v_cvt_pk_bf16_f32 v92, v92, v93
	v_cvt_pk_bf16_f32 v93, v94, v95
	v_cvt_pk_bf16_f32 v94, v88, v89
	v_cvt_pk_bf16_f32 v95, v90, v91
	v_add_u32_e32 v149, 0x20000, v148
	global_store_dwordx4 v149, v[92:95], s[12:13]
	s_waitcnt vmcnt(15)
	v_lshlrev_b32_e32 v230, 16, v186
	v_and_b32_e32 v186, 0xffff0000, v186
	v_lshlrev_b32_e32 v231, 16, v187
	v_and_b32_e32 v187, 0xffff0000, v187
	v_lshlrev_b32_e32 v232, 16, v188
	v_and_b32_e32 v188, 0xffff0000, v188
	v_lshlrev_b32_e32 v233, 16, v189
	v_and_b32_e32 v189, 0xffff0000, v189
	v_mul_f32_e32 v84, v84, v230
	v_mul_f32_e32 v85, v85, v186
	v_mul_f32_e32 v86, v86, v231
	v_mul_f32_e32 v87, v87, v187
	v_mul_f32_e32 v80, v80, v232
	v_mul_f32_e32 v81, v81, v188
	v_mul_f32_e32 v82, v82, v233
	v_mul_f32_e32 v83, v83, v189
	v_cvt_pk_bf16_f32 v84, v84, v85
	v_cvt_pk_bf16_f32 v85, v86, v87
	v_cvt_pk_bf16_f32 v86, v80, v81
	v_cvt_pk_bf16_f32 v87, v82, v83
	global_store_dwordx4 v149, v[84:87], s[12:13] offset:256
	s_waitcnt vmcnt(15)
; __device__ __forceinline__ void store8(bf16_t* dst, const float* v) { u32x4 w; w.x = pk2(v[0], v[1]); w.y = pk2(v[2], v[3]); w.z = pk2(v[4], v[5]); w.w = pk2(v[6], v[7]); *(u32x4*)dst = w; }
; __device__ __forceinline__ void load8(const bf16_t* src, float* v) { const u32x4 w = *(const u32x4*)src; v[0] = bf_lo(w.x); v[1] = bf_hi(w.x); v[2] = bf_lo(w.y); v[3] = bf_hi(w.y); v[4] = bf_lo(w.z); v[5] = bf_hi(w.z); v[6] = bf_lo(w.w); v[7] = bf_hi(w.w); }
;     __device__ __forceinline__ void operator()(const pg8::f32x4 (&acc)[2][2][4][2], const pg8::Unit& u, int wr, int wc, int fr, int fq) const {
;     ...
; #pragma unroll
;         for (int ai = 0; ai < 2; ++ai)
; #pragma unroll
;             for (int m = 0; m < 4; ++m) {
;                 const int row = u.pm * 256 + ai * 128 + wr * 64 + m * 16 + fr;
;                 const int bb = row >> 13, ss = row & 8191;
;                 float ssq = 0.f;
;                 float rs = 1.f;
;                 if constexpr (KIND == EK_Q || KIND == EK_KV) rs = __builtin_amdgcn_rsqf(a.ssq0[row] * (1.f / 512.f) + EPS);
;                 if constexpr (KIND == EK_FIN) rs = __builtin_amdgcn_rsqf(a.ssq0[row] * (1.f / 2048.f) + EPS);
; #pragma unroll
;                 for (int bj = 0; bj < 2; ++bj) {
;                     const int cl = bj * 128 + wc * 32 + fq * 8;
;                     float v[8];
; #pragma unroll
;                     for (int j = 0; j < 4; ++j) { v[j] = acc[ai][bj][m][0][j]; v[4 + j] = acc[ai][bj][m][1][j]; }
;     ...
;                     } else if constexpr (KIND == EK_MIX1) {
;                         const size_t off = (size_t)row * 2048 + pn * 256 + cl; float g[8]; load8(a.g0 + off, g);
; #pragma unroll
;                         for (int j = 0; j < 8; ++j) v[j] *= g[j];
;                         store8(a.o0 + off, v);
	v_lshlrev_b32_e32 v230, 16, v190
	v_and_b32_e32 v190, 0xffff0000, v190
	v_lshlrev_b32_e32 v231, 16, v191
	v_and_b32_e32 v191, 0xffff0000, v191
	v_lshlrev_b32_e32 v232, 16, v192
	v_and_b32_e32 v192, 0xffff0000, v192
	v_lshlrev_b32_e32 v233, 16, v193
	v_and_b32_e32 v193, 0xffff0000, v193
	v_mul_f32_e32 v76, v76, v230
	v_mul_f32_e32 v77, v77, v190
	v_mul_f32_e32 v78, v78, v231
	v_mul_f32_e32 v79, v79, v191
	v_mul_f32_e32 v72, v72, v232
	v_mul_f32_e32 v73, v73, v192
	v_mul_f32_e32 v74, v74, v233
	v_mul_f32_e32 v75, v75, v193
	v_cvt_pk_bf16_f32 v76, v76, v77
	v_cvt_pk_bf16_f32 v77, v78, v79
	v_cvt_pk_bf16_f32 v78, v72, v73
	v_cvt_pk_bf16_f32 v79, v74, v75
	v_add_u32_e32 v149, 0x30000, v148
	global_store_dwordx4 v149, v[76:79], s[12:13]
	s_waitcnt vmcnt(15)
	v_lshlrev_b32_e32 v230, 16, v194
	v_and_b32_e32 v194, 0xffff0000, v194
	v_lshlrev_b32_e32 v231, 16, v195
	v_and_b32_e32 v195, 0xffff0000, v195
	v_lshlrev_b32_e32 v232, 16, v196
	v_and_b32_e32 v196, 0xffff0000, v196
	v_lshlrev_b32_e32 v233, 16, v197
	v_and_b32_e32 v197, 0xffff0000, v197
	v_mul_f32_e32 v68, v68, v230
	v_mul_f32_e32 v69, v69, v194
	v_mul_f32_e32 v70, v70, v231
	v_mul_f32_e32 v71, v71, v195
	v_mul_f32_e32 v64, v64, v232
	v_mul_f32_e32 v65, v65, v196
	v_mul_f32_e32 v66, v66, v233
	v_mul_f32_e32 v67, v67, v197
	v_cvt_pk_bf16_f32 v68, v68, v69
	v_cvt_pk_bf16_f32 v69, v70, v71
	v_cvt_pk_bf16_f32 v70, v64, v65
	v_cvt_pk_bf16_f32 v71, v66, v67
	global_store_dwordx4 v149, v[68:71], s[12:13] offset:256
	s_waitcnt vmcnt(15)
	v_lshlrev_b32_e32 v230, 16, v198
	v_and_b32_e32 v198, 0xffff0000, v198
	v_lshlrev_b32_e32 v231, 16, v199
	v_and_b32_e32 v199, 0xffff0000, v199
	v_lshlrev_b32_e32 v232, 16, v200
	v_and_b32_e32 v200, 0xffff0000, v200
	v_lshlrev_b32_e32 v233, 16, v201
	v_and_b32_e32 v201, 0xffff0000, v201
	v_mul_f32_e32 v60, v60, v230
	v_mul_f32_e32 v61, v61, v198
	v_mul_f32_e32 v62, v62, v231
	v_mul_f32_e32 v63, v63, v199
	v_mul_f32_e32 v56, v56, v232
	v_mul_f32_e32 v57, v57, v200
	v_mul_f32_e32 v58, v58, v233
	v_mul_f32_e32 v59, v59, v201
	v_cvt_pk_bf16_f32 v60, v60, v61
	v_cvt_pk_bf16_f32 v61, v62, v63
	v_cvt_pk_bf16_f32 v62, v56, v57
	v_cvt_pk_bf16_f32 v63, v58, v59
	v_add_u32_e32 v149, 0x80000, v148
	global_store_dwordx4 v149, v[60:63], s[12:13]
	s_waitcnt vmcnt(15)
	v_lshlrev_b32_e32 v230, 16, v202
	v_and_b32_e32 v202, 0xffff0000, v202
	v_lshlrev_b32_e32 v231, 16, v203
	v_and_b32_e32 v203, 0xffff0000, v203
	v_lshlrev_b32_e32 v232, 16, v204
	v_and_b32_e32 v204, 0xffff0000, v204
	v_lshlrev_b32_e32 v233, 16, v205
	v_and_b32_e32 v205, 0xffff0000, v205
	v_mul_f32_e32 v52, v52, v230
	v_mul_f32_e32 v53, v53, v202
	v_mul_f32_e32 v54, v54, v231
	v_mul_f32_e32 v55, v55, v203
	v_mul_f32_e32 v48, v48, v232
	v_mul_f32_e32 v49, v49, v204
	v_mul_f32_e32 v50, v50, v233
	v_mul_f32_e32 v51, v51, v205
	v_cvt_pk_bf16_f32 v52, v52, v53
	v_cvt_pk_bf16_f32 v53, v54, v55
	v_cvt_pk_bf16_f32 v54, v48, v49
	v_cvt_pk_bf16_f32 v55, v50, v51
	global_store_dwordx4 v149, v[52:55], s[12:13] offset:256
	s_waitcnt vmcnt(15)
	v_lshlrev_b32_e32 v230, 16, v206
	v_and_b32_e32 v206, 0xffff0000, v206
	v_lshlrev_b32_e32 v231, 16, v207
	v_and_b32_e32 v207, 0xffff0000, v207
	v_lshlrev_b32_e32 v232, 16, v208
	v_and_b32_e32 v208, 0xffff0000, v208
	v_lshlrev_b32_e32 v233, 16, v209
	v_and_b32_e32 v209, 0xffff0000, v209
	v_mul_f32_e32 v44, v44, v230
	v_mul_f32_e32 v45, v45, v206
	v_mul_f32_e32 v46, v46, v231
	v_mul_f32_e32 v47, v47, v207
	v_mul_f32_e32 v40, v40, v232
	v_mul_f32_e32 v41, v41, v208
	v_mul_f32_e32 v42, v42, v233
	v_mul_f32_e32 v43, v43, v209
	v_cvt_pk_bf16_f32 v44, v44, v45
	v_cvt_pk_bf16_f32 v45, v46, v47
	v_cvt_pk_bf16_f32 v46, v40, v41
	v_cvt_pk_bf16_f32 v47, v42, v43
	v_add_u32_e32 v149, 0x90000, v148
	global_store_dwordx4 v149, v[44:47], s[12:13]
	s_waitcnt vmcnt(15)
; #define PG8_BAR __builtin_amdgcn_s_barrier()
; __device__ __forceinline__ void store8(bf16_t* dst, const float* v) { u32x4 w; w.x = pk2(v[0], v[1]); w.y = pk2(v[2], v[3]); w.z = pk2(v[4], v[5]); w.w = pk2(v[6], v[7]); *(u32x4*)dst = w; }
; template <class Epi, class Sched, bool ALIGN_EPI = false, bool SP2 = false>
; __device__ __forceinline__ void gemm_phase(PG8_LAS unsigned char* lds, const Gemm g, const Sched& S, const Epi& E) {
;     ...
;         if (!has_next) break;
; #pragma unroll
;         for (int a = 0; a < 2; ++a)
; #pragma unroll
;             for (int b = 0; b < 2; ++b)
; #pragma unroll
;                 for (int m = 0; m < 4; ++m)
; #pragma unroll
;                     for (int n = 0; n < 2; ++n) acc[a][b][m][n] = (f32x4){0.f, 0.f, 0.f, 0.f};
;         cur = nxt; cA = nA; cB = nB; ++ui;
;         if constexpr (ALIGN_EPI) { if (wr == 1) PG8_BAR; }
;     __device__ __forceinline__ void operator()(const pg8::f32x4 (&acc)[2][2][4][2], const pg8::Unit& u, int wr, int wc, int fr, int fq) const {
;     ...
; #pragma unroll
;         for (int ai = 0; ai < 2; ++ai)
; #pragma unroll
;             for (int m = 0; m < 4; ++m) {
;                 const int row = u.pm * 256 + ai * 128 + wr * 64 + m * 16 + fr;
;                 const int bb = row >> 13, ss = row & 8191;
;                 float ssq = 0.f;
;                 float rs = 1.f;
;                 if constexpr (KIND == EK_Q || KIND == EK_KV) rs = __builtin_amdgcn_rsqf(a.ssq0[row] * (1.f / 512.f) + EPS);
;                 if constexpr (KIND == EK_FIN) rs = __builtin_amdgcn_rsqf(a.ssq0[row] * (1.f / 2048.f) + EPS);
; #pragma unroll
;                 for (int bj = 0; bj < 2; ++bj) {
;                     const int cl = bj * 128 + wc * 32 + fq * 8;
;                     float v[8];
; #pragma unroll
;                     for (int j = 0; j < 4; ++j) { v[j] = acc[ai][bj][m][0][j]; v[4 + j] = acc[ai][bj][m][1][j]; }
;     ...
;                     } else if constexpr (KIND == EK_MIX1) {
;                         const size_t off = (size_t)row * 2048 + pn * 256 + cl; float g[8]; load8(a.g0 + off, g);
; #pragma unroll
;                         for (int j = 0; j < 8; ++j) v[j] *= g[j];
;                         store8(a.o0 + off, v);
	v_lshlrev_b32_e32 v230, 16, v210
	v_and_b32_e32 v210, 0xffff0000, v210
	v_lshlrev_b32_e32 v231, 16, v211
	v_and_b32_e32 v211, 0xffff0000, v211
	v_lshlrev_b32_e32 v232, 16, v212
	v_and_b32_e32 v212, 0xffff0000, v212
	v_lshlrev_b32_e32 v233, 16, v213
	v_and_b32_e32 v213, 0xffff0000, v213
	v_mul_f32_e32 v36, v36, v230
	v_mul_f32_e32 v37, v37, v210
	v_mul_f32_e32 v38, v38, v231
	v_mul_f32_e32 v39, v39, v211
	v_mul_f32_e32 v32, v32, v232
	v_mul_f32_e32 v33, v33, v212
	v_mul_f32_e32 v34, v34, v233
	v_mul_f32_e32 v35, v35, v213
	v_cvt_pk_bf16_f32 v36, v36, v37
	v_cvt_pk_bf16_f32 v37, v38, v39
	v_cvt_pk_bf16_f32 v38, v32, v33
	v_cvt_pk_bf16_f32 v39, v34, v35
	global_store_dwordx4 v149, v[36:39], s[12:13] offset:256
	s_waitcnt vmcnt(15)
	v_lshlrev_b32_e32 v230, 16, v214
	v_and_b32_e32 v214, 0xffff0000, v214
	v_lshlrev_b32_e32 v231, 16, v215
	v_and_b32_e32 v215, 0xffff0000, v215
	v_lshlrev_b32_e32 v232, 16, v216
	v_and_b32_e32 v216, 0xffff0000, v216
	v_lshlrev_b32_e32 v233, 16, v217
	v_and_b32_e32 v217, 0xffff0000, v217
	v_mul_f32_e32 v28, v28, v230
	v_mul_f32_e32 v29, v29, v214
	v_mul_f32_e32 v30, v30, v231
	v_mul_f32_e32 v31, v31, v215
	v_mul_f32_e32 v24, v24, v232
	v_mul_f32_e32 v25, v25, v216
	v_mul_f32_e32 v26, v26, v233
	v_mul_f32_e32 v27, v27, v217
	v_cvt_pk_bf16_f32 v28, v28, v29
	v_cvt_pk_bf16_f32 v29, v30, v31
	v_cvt_pk_bf16_f32 v30, v24, v25
	v_cvt_pk_bf16_f32 v31, v26, v27
	v_add_u32_e32 v149, 0xa0000, v148
	global_store_dwordx4 v149, v[28:31], s[12:13]
	s_waitcnt vmcnt(15)
	v_lshlrev_b32_e32 v230, 16, v218
	v_and_b32_e32 v218, 0xffff0000, v218
	v_lshlrev_b32_e32 v231, 16, v219
	v_and_b32_e32 v219, 0xffff0000, v219
	v_lshlrev_b32_e32 v232, 16, v220
	v_and_b32_e32 v220, 0xffff0000, v220
	v_lshlrev_b32_e32 v233, 16, v221
	v_and_b32_e32 v221, 0xffff0000, v221
	v_mul_f32_e32 v20, v20, v230
	v_mul_f32_e32 v21, v21, v218
	v_mul_f32_e32 v22, v22, v231
	v_mul_f32_e32 v23, v23, v219
	v_mul_f32_e32 v16, v16, v232
	v_mul_f32_e32 v17, v17, v220
	v_mul_f32_e32 v18, v18, v233
	v_mul_f32_e32 v19, v19, v221
	v_cvt_pk_bf16_f32 v20, v20, v21
	v_cvt_pk_bf16_f32 v21, v22, v23
	v_cvt_pk_bf16_f32 v22, v16, v17
	v_cvt_pk_bf16_f32 v23, v18, v19
	global_store_dwordx4 v149, v[20:23], s[12:13] offset:256
	s_waitcnt vmcnt(15)
	v_lshlrev_b32_e32 v230, 16, v222
	v_and_b32_e32 v222, 0xffff0000, v222
	v_lshlrev_b32_e32 v231, 16, v223
	v_and_b32_e32 v223, 0xffff0000, v223
	v_lshlrev_b32_e32 v232, 16, v224
	v_and_b32_e32 v224, 0xffff0000, v224
	v_lshlrev_b32_e32 v233, 16, v225
	v_and_b32_e32 v225, 0xffff0000, v225
	v_mul_f32_e32 v12, v12, v230
	v_mul_f32_e32 v13, v13, v222
	v_mul_f32_e32 v14, v14, v231
	v_mul_f32_e32 v15, v15, v223
	v_mul_f32_e32 v8, v8, v232
	v_mul_f32_e32 v9, v9, v224
	v_mul_f32_e32 v10, v10, v233
	v_mul_f32_e32 v11, v11, v225
	v_cvt_pk_bf16_f32 v12, v12, v13
	v_cvt_pk_bf16_f32 v13, v14, v15
	v_cvt_pk_bf16_f32 v14, v8, v9
	v_cvt_pk_bf16_f32 v15, v10, v11
	v_add_u32_e32 v149, 0xb0000, v148
	global_store_dwordx4 v149, v[12:15], s[12:13]
	s_waitcnt vmcnt(15)
	v_lshlrev_b32_e32 v230, 16, v226
	v_and_b32_e32 v226, 0xffff0000, v226
	v_lshlrev_b32_e32 v231, 16, v227
	v_and_b32_e32 v227, 0xffff0000, v227
	v_lshlrev_b32_e32 v232, 16, v228
	v_and_b32_e32 v228, 0xffff0000, v228
	v_lshlrev_b32_e32 v233, 16, v229
	v_and_b32_e32 v229, 0xffff0000, v229
	v_mul_f32_e32 v4, v4, v230
	v_mul_f32_e32 v5, v5, v226
	v_mul_f32_e32 v6, v6, v231
	v_mul_f32_e32 v7, v7, v227
	v_mul_f32_e32 v0, v0, v232
	v_mul_f32_e32 v1, v1, v228
	v_mul_f32_e32 v2, v2, v233
	v_mul_f32_e32 v3, v3, v229
	v_cvt_pk_bf16_f32 v4, v4, v5
	v_cvt_pk_bf16_f32 v5, v6, v7
	v_cvt_pk_bf16_f32 v6, v0, v1
	v_cvt_pk_bf16_f32 v7, v2, v3
	global_store_dwordx4 v149, v[4:7], s[12:13] offset:256
	s_andn2_b64 vcc, exec, s[6:7]
	s_mov_b64 s[6:7], -1
	s_cbranch_vccnz .LBB0_1041
	s_andn2_b64 vcc, exec, s[10:11]
	s_cbranch_vccnz .LBB0_1040
	s_barrier
	s_branch .LBB0_1040
